# grid barrier: waiting workgroups poll the top-level generation word directly (per-XCD generation relay hop removed)
# baseline (speedup 1.0000x reference)
.LBB0_557:
	s_or_b64 exec, exec, s[6:7]
	v_cvt_f32_u32_e32 v4, v2
	s_waitcnt vmcnt(0)
	v_readfirstlane_b32 s1, v3
	v_sub_u32_e32 v3, 0, v2
	v_rcp_iflag_f32_e32 v4, v4
	v_add_u32_e32 v5, s1, v1
	v_mul_f32_e32 v4, 0x4f7ffffe, v4
	v_cvt_u32_f32_e32 v4, v4
	v_mul_lo_u32 v1, v3, v4
	v_mul_hi_u32 v1, v4, v1
	v_add_u32_e32 v1, v4, v1
	v_mul_hi_u32 v1, v5, v1
	v_mul_lo_u32 v3, v1, v2
	v_sub_u32_e32 v3, v5, v3
	v_add_u32_e32 v4, 1, v1
	v_cmp_ge_u32_e32 vcc, v3, v2
	s_nop 1
	v_cndmask_b32_e32 v1, v1, v4, vcc
	v_sub_u32_e32 v4, v3, v2
	v_cndmask_b32_e32 v3, v3, v4, vcc
	v_add_u32_e32 v4, 1, v1
	v_cmp_ge_u32_e32 vcc, v3, v2
	v_add_u32_e32 v3, 1, v5
	s_nop 0
	v_cndmask_b32_e32 v1, v1, v4, vcc
	v_mul_lo_u32 v4, v2, v1
	v_add_u32_e32 v2, v4, v2
	v_cmp_ne_u32_e32 vcc, v3, v2
	s_and_saveexec_b64 s[6:7], vcc
	s_xor_b64 s[6:7], exec, s[6:7]
	s_cbranch_execz .LBB0_571
	v_readlane_b32 s8, v253, 10
	v_readlane_b32 s9, v253, 11
	s_waitcnt lgkmcnt(0)
	s_nop 3
	global_load_dword v0, v51, s[8:9] sc1
	s_waitcnt vmcnt(0)
	v_cmp_eq_u32_e32 vcc, v0, v1
	s_and_saveexec_b64 s[12:13], vcc
	s_cbranch_execz .LBB0_570
	s_mov_b32 s1, 1
	s_mov_b64 s[26:27], 0
	s_branch .LBB0_561

.LBB0_563:
	v_readlane_b32 s8, v253, 10
	v_readlane_b32 s9, v253, 11
	s_add_i32 s1, s1, 1
	s_mov_b64 s[40:41], -1
	s_nop 2
	global_load_dword v0, v51, s[8:9] sc1
	s_waitcnt vmcnt(0)
	v_cmp_ne_u32_e32 vcc, v0, v1
	s_orn2_b64 s[38:39], vcc, exec
	s_branch .LBB0_560

.LBB0_588:
	s_or_b64 exec, exec, s[6:7]
	s_mov_b64 s[6:7], exec
	v_mbcnt_lo_u32_b32 v0, s6, 0
	v_mbcnt_hi_u32_b32 v0, s7, v0
	v_cmp_eq_u32_e32 vcc, 0, v0
	s_waitcnt vmcnt(0)
	buffer_inv sc1
	s_and_saveexec_b64 s[12:13], vcc
	s_cbranch_execz .LBB0_590
	s_bcnt1_i32_b64 s1, s[6:7]
	v_readlane_b32 s6, v253, 6
	v_mov_b32_e32 v0, s1
	v_readlane_b32 s7, v253, 7
	s_nop 4
	s_nop 0

.LBB0_2215:
	s_or_b64 exec, exec, s[6:7]
	v_cvt_f32_u32_e32 v4, v2
	s_waitcnt vmcnt(0)
	v_readfirstlane_b32 s0, v3
	v_sub_u32_e32 v3, 0, v2
	v_rcp_iflag_f32_e32 v4, v4
	v_add_u32_e32 v5, s0, v1
	v_mul_f32_e32 v4, 0x4f7ffffe, v4
	v_cvt_u32_f32_e32 v4, v4
	v_mul_lo_u32 v1, v3, v4
	v_mul_hi_u32 v1, v4, v1
	v_add_u32_e32 v1, v4, v1
	v_mul_hi_u32 v1, v5, v1
	v_mul_lo_u32 v3, v1, v2
	v_sub_u32_e32 v3, v5, v3
	v_add_u32_e32 v4, 1, v1
	v_cmp_ge_u32_e32 vcc, v3, v2
	s_nop 1
	v_cndmask_b32_e32 v1, v1, v4, vcc
	v_sub_u32_e32 v4, v3, v2
	v_cndmask_b32_e32 v3, v3, v4, vcc
	v_add_u32_e32 v4, 1, v1
	v_cmp_ge_u32_e32 vcc, v3, v2
	v_add_u32_e32 v3, 1, v5
	s_nop 0
	v_cndmask_b32_e32 v1, v1, v4, vcc
	v_mul_lo_u32 v4, v2, v1
	v_add_u32_e32 v2, v4, v2
	v_cmp_ne_u32_e32 vcc, v3, v2
	s_and_saveexec_b64 s[0:1], vcc
	s_xor_b64 s[6:7], exec, s[0:1]
	s_cbranch_execz .LBB0_2246
	v_readlane_b32 s0, v253, 10
	v_readlane_b32 s1, v253, 11
	s_waitcnt lgkmcnt(0)
	s_nop 3
	global_load_dword v0, v51, s[0:1] sc1
	s_waitcnt vmcnt(0)
	v_cmp_eq_u32_e32 vcc, v0, v1
	s_and_saveexec_b64 s[12:13], vcc
	s_cbranch_execz .LBB0_2245
	s_mov_b32 s0, 1
	s_mov_b64 s[26:27], 0
	s_branch .LBB0_2219

.LBB0_2221:
	v_readlane_b32 s8, v253, 10
	v_readlane_b32 s9, v253, 11
	s_add_i32 s0, s0, 1
	s_mov_b64 s[40:41], -1
	s_nop 2
	global_load_dword v0, v51, s[8:9] sc1
	s_waitcnt vmcnt(0)
	v_cmp_ne_u32_e32 vcc, v0, v1
	s_orn2_b64 s[38:39], vcc, exec
	s_branch .LBB0_2218

.LBB0_2232:
	s_or_b64 exec, exec, s[12:13]
	v_cvt_f32_u32_e32 v4, v2
	s_waitcnt vmcnt(0)
	v_readfirstlane_b32 s0, v3
	v_sub_u32_e32 v3, 0, v2
	v_rcp_iflag_f32_e32 v4, v4
	v_add_u32_e32 v5, s0, v1
	v_mul_f32_e32 v4, 0x4f7ffffe, v4
	v_cvt_u32_f32_e32 v4, v4
	v_mul_lo_u32 v1, v3, v4
	v_mul_hi_u32 v1, v4, v1
	v_add_u32_e32 v1, v4, v1
	v_mul_hi_u32 v1, v5, v1
	v_mul_lo_u32 v3, v1, v2
	v_sub_u32_e32 v3, v5, v3
	v_add_u32_e32 v4, 1, v1
	v_cmp_ge_u32_e32 vcc, v3, v2
	s_nop 1
	v_cndmask_b32_e32 v1, v1, v4, vcc
	v_sub_u32_e32 v4, v3, v2
	v_cndmask_b32_e32 v3, v3, v4, vcc
	v_add_u32_e32 v4, 1, v1
	v_cmp_ge_u32_e32 vcc, v3, v2
	v_add_u32_e32 v3, 1, v5
	s_nop 0
	v_cndmask_b32_e32 v1, v1, v4, vcc
	v_mul_lo_u32 v4, v2, v1
	v_add_u32_e32 v2, v4, v2
	v_cmp_ne_u32_e32 vcc, v3, v2
	s_and_saveexec_b64 s[0:1], vcc
	s_xor_b64 s[12:13], exec, s[0:1]
	s_cbranch_execz .LBB0_2263
	v_readlane_b32 s0, v253, 10
	v_readlane_b32 s1, v253, 11
	s_waitcnt lgkmcnt(0)
	s_nop 3
	global_load_dword v0, v51, s[0:1] sc1
	s_waitcnt vmcnt(0)
	v_cmp_eq_u32_e32 vcc, v0, v1
	s_and_saveexec_b64 s[26:27], vcc
	s_cbranch_execz .LBB0_2262
	s_mov_b32 s0, 1
	s_mov_b64 s[34:35], 0
	s_branch .LBB0_2236

.LBB0_2238:
	v_readlane_b32 s8, v253, 10
	v_readlane_b32 s9, v253, 11
	s_add_i32 s0, s0, 1
	s_mov_b64 s[46:47], -1
	s_nop 2
	global_load_dword v0, v51, s[8:9] sc1
	s_waitcnt vmcnt(0)
	v_cmp_ne_u32_e32 vcc, v0, v1
	s_orn2_b64 s[40:41], vcc, exec
	s_branch .LBB0_2235

.LBB0_2280:
	s_or_b64 exec, exec, s[6:7]
	s_mov_b64 s[6:7], exec
	v_mbcnt_lo_u32_b32 v0, s6, 0
	v_mbcnt_hi_u32_b32 v0, s7, v0
	v_cmp_eq_u32_e32 vcc, 0, v0
	s_waitcnt vmcnt(0)
	buffer_inv sc1
	s_and_saveexec_b64 s[12:13], vcc
	s_cbranch_execz .LBB0_2282
	s_bcnt1_i32_b64 s0, s[6:7]
	v_mov_b32_e32 v0, s0
	v_readlane_b32 s0, v253, 6
	v_readlane_b32 s1, v253, 7
	s_nop 4
	s_nop 0

.LBB0_2301:
	s_or_b64 exec, exec, s[12:13]
	s_mov_b64 s[12:13], exec
	v_mbcnt_lo_u32_b32 v0, s12, 0
	v_mbcnt_hi_u32_b32 v0, s13, v0
	v_cmp_eq_u32_e32 vcc, 0, v0
	s_waitcnt vmcnt(0)
	buffer_inv sc1
	s_and_saveexec_b64 s[26:27], vcc
	s_cbranch_execz .LBB0_2303
	s_bcnt1_i32_b64 s0, s[12:13]
	v_mov_b32_e32 v0, s0
	v_readlane_b32 s0, v253, 6
	v_readlane_b32 s1, v253, 7
	s_nop 4
	s_nop 0
